# adds: MLA and stick-breaking epilogues pair half-wave pieces with permlane32 swaps and store 16 bytes per lane (4 dwordx4 instead of 8 dwordx2 per unit)
# speedup vs baseline: 1.0127x; 1.0127x over previous
; __device__ __forceinline__ unsigned cvtpk(float lo, float hi) { f32x2_t v = {lo, hi}; bf16x2_t b = __builtin_convertvector(v, bf16x2_t); return __builtin_bit_cast(unsigned, b); }
; template <bool DRY> __device__ __forceinline__ void sb_unit(int b, int h, int qi, bf16_t* Pm, const bf16_t* VT) {
;     ...
; #pragma unroll
;     for (int g = 0; g < 4; ++g) {
;         u32x2 w0, w1;
;         w0.x = cvtpk(o0[4 * g], o0[4 * g + 1]); w0.y = cvtpk(o0[4 * g + 2], o0[4 * g + 3]);
;         w1.x = cvtpk(o1[4 * g], o1[4 * g + 1]); w1.y = cvtpk(o1[4 * g + 2], o1[4 * g + 3]);
;         if (!DRY || R == 1234.56789f) { *(u32x2*)(qrow + 8 * g + 4 * hi) = w0; *(u32x2*)(qrow + 32 + 8 * g + 4 * hi) = w1; }
;     }
.Lsbl_exit:
	s_waitcnt vmcnt(0)
	s_or_b64 exec, exec, s[34:35]
	v_lshlrev_b32_e32 v0, 2, v86
	v_mov_b32_e32 v1, v2
	v_lshl_add_u64 v[0:1], v[84:85], 0, v[0:1]
	s_nop 4
	v_cvt_pk_bf16_f32 v4, v4, v5
	v_cvt_pk_bf16_f32 v5, v6, v7
	v_cvt_pk_bf16_f32 v6, v8, v9
	v_cvt_pk_bf16_f32 v7, v10, v11
	v_cvt_pk_bf16_f32 v8, v12, v13
	v_cvt_pk_bf16_f32 v9, v14, v15
	v_cvt_pk_bf16_f32 v10, v16, v17
	v_cvt_pk_bf16_f32 v11, v18, v19
	v_cvt_pk_bf16_f32 v20, v20, v21
	v_cvt_pk_bf16_f32 v21, v22, v23
	v_cvt_pk_bf16_f32 v22, v24, v25
	v_cvt_pk_bf16_f32 v23, v26, v27
	v_cvt_pk_bf16_f32 v24, v28, v29
	v_cvt_pk_bf16_f32 v25, v30, v31
	v_cvt_pk_bf16_f32 v26, v32, v33
	v_cvt_pk_bf16_f32 v27, v34, v35
	v_permlane32_swap_b32_e32 v4, v6
	v_permlane32_swap_b32_e32 v5, v7
	v_permlane32_swap_b32_e32 v8, v10
	v_permlane32_swap_b32_e32 v9, v11
	v_permlane32_swap_b32_e32 v20, v22
	v_permlane32_swap_b32_e32 v21, v23
	v_permlane32_swap_b32_e32 v24, v26
	v_permlane32_swap_b32_e32 v25, v27
	global_store_dwordx4 v[0:1], v[4:7], off offset:1280
	global_store_dwordx4 v[0:1], v[8:11], off offset:1312
	global_store_dwordx4 v[0:1], v[20:23], off offset:1344
	global_store_dwordx4 v[0:1], v[24:27], off offset:1376
	v_add_u32_e32 v3, s26, v3
	s_movk_i32 s4, 0x1fff
	v_cmp_lt_i32_e32 vcc, s4, v3
	s_or_b64 s[40:41], vcc, s[40:41]
	v_add_u16_e32 v87, s26, v87
	s_andn2_b64 exec, exec, s[40:41]
	s_cbranch_execnz .LBB0_741

; __device__ __forceinline__ unsigned cvtpk(float lo, float hi) { f32x2_t v = {lo, hi}; bf16x2_t b = __builtin_convertvector(v, bf16x2_t); return __builtin_bit_cast(unsigned, b); }
; template <bool DRY> __device__ __forceinline__ void mla_unit(LAS unsigned char* lds, int b, int h, int qb, const bf16_t* Q, const bf16_t* Kn, const bf16_t* Pm, const bf16_t* VT, bf16_t* Y) {
;     ...
;     const float l = l_run + __shfl_xor(l_run, 32); const float inv = 1.f / l;
;     bf16_t* yrow = Y + qtok * 768 + h * 64;
; #pragma unroll
;     for (int g = 0; g < 4; ++g) {
;         u32x2 w0, w1;
;         w0.x = cvtpk(o0[4 * g] * inv, o0[4 * g + 1] * inv); w0.y = cvtpk(o0[4 * g + 2] * inv, o0[4 * g + 3] * inv);
;         w1.x = cvtpk(o1[4 * g] * inv, o1[4 * g + 1] * inv); w1.y = cvtpk(o1[4 * g + 2] * inv, o1[4 * g + 3] * inv);
;         if (!DRY || l == 1234.56789f) { *(u32x2*)(yrow + 8 * g + 4 * hi) = w0; *(u32x2*)(yrow + 32 + 8 * g + 4 * hi) = w1; }
;     }
.LBB0_800:
	v_xor_b32_e32 v0, 32, v238
	v_add_u32_e32 v1, 64, v239
	v_cmp_lt_i32_e32 vcc, v0, v1
	v_mov_b32_e32 v107, v2
	s_add_i32 s55, s55, 1
	v_cndmask_b32_e32 v0, v238, v0, vcc
	v_lshlrev_b32_e32 v0, 2, v0
	ds_bpermute_b32 v0, v0, v121
	s_cmp_eq_u32 s55, 4
	s_waitcnt lgkmcnt(0)
	v_add_f32_e32 v0, v121, v0
	v_div_scale_f32 v1, s[22:23], v0, v0, 1.0
	v_rcp_f32_e32 v3, v1
	s_nop 0
	v_fma_f32 v36, -v1, v3, 1.0
	v_fmac_f32_e32 v3, v36, v3
	v_div_scale_f32 v36, vcc, 1.0, v0, 1.0
	v_mul_f32_e32 v37, v36, v3
	v_fma_f32 v38, -v1, v37, v36
	v_fmac_f32_e32 v37, v38, v3
	v_fma_f32 v1, -v1, v37, v36
	v_div_fmas_f32 v1, v1, v3, v37
	v_div_fixup_f32 v0, v1, v0, 1.0
	v_pk_mul_f32 v[20:21], v[20:21], v[0:1] op_sel_hi:[1,0]
	v_pk_mul_f32 v[22:23], v[22:23], v[0:1] op_sel_hi:[1,0]
	v_pk_mul_f32 v[24:25], v[24:25], v[0:1] op_sel_hi:[1,0]
	v_pk_mul_f32 v[26:27], v[26:27], v[0:1] op_sel_hi:[1,0]
	v_pk_mul_f32 v[28:29], v[28:29], v[0:1] op_sel_hi:[1,0]
	v_pk_mul_f32 v[30:31], v[30:31], v[0:1] op_sel_hi:[1,0]
	v_pk_mul_f32 v[32:33], v[32:33], v[0:1] op_sel_hi:[1,0]
	v_pk_mul_f32 v[34:35], v[34:35], v[0:1] op_sel_hi:[1,0]
	v_pk_mul_f32 v[4:5], v[4:5], v[0:1] op_sel_hi:[1,0]
	v_pk_mul_f32 v[6:7], v[6:7], v[0:1] op_sel_hi:[1,0]
	v_pk_mul_f32 v[8:9], v[8:9], v[0:1] op_sel_hi:[1,0]
	v_pk_mul_f32 v[10:11], v[10:11], v[0:1] op_sel_hi:[1,0]
	v_pk_mul_f32 v[12:13], v[12:13], v[0:1] op_sel_hi:[1,0]
	v_pk_mul_f32 v[14:15], v[14:15], v[0:1] op_sel_hi:[1,0]
	v_pk_mul_f32 v[16:17], v[16:17], v[0:1] op_sel_hi:[1,0]
	v_pk_mul_f32 v[18:19], v[18:19], v[0:1] op_sel_hi:[1,0]
	v_lshl_add_u64 v[36:37], v[106:107], 1, v[104:105]
	v_cvt_pk_bf16_f32 v20, v20, v21
	v_cvt_pk_bf16_f32 v21, v22, v23
	v_cvt_pk_bf16_f32 v22, v24, v25
	v_cvt_pk_bf16_f32 v23, v26, v27
	v_cvt_pk_bf16_f32 v24, v28, v29
	v_cvt_pk_bf16_f32 v25, v30, v31
	v_cvt_pk_bf16_f32 v26, v32, v33
	v_cvt_pk_bf16_f32 v27, v34, v35
	v_cvt_pk_bf16_f32 v4, v4, v5
	v_cvt_pk_bf16_f32 v5, v6, v7
	v_cvt_pk_bf16_f32 v6, v8, v9
	v_cvt_pk_bf16_f32 v7, v10, v11
	v_cvt_pk_bf16_f32 v8, v12, v13
	v_cvt_pk_bf16_f32 v9, v14, v15
	v_cvt_pk_bf16_f32 v10, v16, v17
	v_cvt_pk_bf16_f32 v11, v18, v19
	v_permlane32_swap_b32_e32 v20, v22
	v_permlane32_swap_b32_e32 v21, v23
	v_permlane32_swap_b32_e32 v24, v26
	v_permlane32_swap_b32_e32 v25, v27
	v_permlane32_swap_b32_e32 v4, v6
	v_permlane32_swap_b32_e32 v5, v7
	v_permlane32_swap_b32_e32 v8, v10
	v_permlane32_swap_b32_e32 v9, v11
	global_store_dwordx4 v[36:37], v[20:23], off
	global_store_dwordx4 v[36:37], v[24:27], off offset:32
	global_store_dwordx4 v[36:37], v[4:7], off offset:64
	global_store_dwordx4 v[36:37], v[8:11], off offset:96
	s_cbranch_scc1 .LBB0_798
